# attention: tile t+2 LDS-DMA issue behind the QK MFMAs (in the MFMA result wait slot) + cvt without copies
# baseline (speedup 1.0000x reference)
; #define LAS __attribute__((address_space(3)))
; #define ATT_SB __builtin_amdgcn_sched_barrier(0)
; template <bool NOSHIFT> __device__ __forceinline__ void diff_attn_unit(LAS unsigned char* lds, bf16_t* proj, const bf16_t* VT, int b, int h, int qb, const AttnConsts ac, const float* gsub, const int tid, bf16_t* obuf, int opitch, int ocol) {
;     ...
; #pragma unroll
;             for (int mt = 0; mt < 2; ++mt)
; #pragma unroll
;                 for (int ks = 0; ks < 4; ++ks) kf[mt][ks] = *(const LAS bf16x8*)(lds + bo + koff[mt][ks]);
;             if constexpr (!NOSHIFT) {
; #pragma unroll
;                 for (int mt = 0; mt < 2; ++mt)
; #pragma unroll
;                     for (int r = 0; r < 16; ++r) p[mt][r] = -ac.Mfix;
;             }
;             ATT_SB;
;             __builtin_amdgcn_s_setprio(1);
; #pragma unroll
;             for (int ks = 0; ks < 4; ++ks)
; #pragma unroll
;                 for (int mt = 0; mt < 2; ++mt) {
;                     if (NOSHIFT && ks == 0) { const f32x16 z = {0.f, 0.f, 0.f, 0.f, 0.f, 0.f, 0.f, 0.f, 0.f, 0.f, 0.f, 0.f, 0.f, 0.f, 0.f, 0.f}; p[mt] = __builtin_amdgcn_mfma_f32_32x32x16_bf16(kf[mt][ks], qf[ks], z, 0, 0, 0); }
;                     else p[mt] = __builtin_amdgcn_mfma_f32_32x32x16_bf16(kf[mt][ks], qf[ks], p[mt], 0, 0, 0);
;                 }
;             __builtin_amdgcn_s_setprio(0);
.LBB1_290:
	s_addk_i32 s14, 0x4000
	s_cmp_gt_u32 s47, s44
	s_cbranch_scc1 .LBB1_297
	s_and_b32 s15, s14, 0xc000
	s_add_i32 s80, s15, 0
	v_add_u32_e32 v7, s80, v179
	v_add_u32_e32 v96, s80, v183
	v_add_u32_e32 v97, s80, v186
	v_add_u32_e32 v98, s80, v187
	ds_read_b128 v[8:11], v7
	ds_read_b128 v[12:15], v7 offset:8192
	ds_read_b128 v[128:131], v96
	ds_read_b128 v[132:135], v96 offset:8192
	ds_read_b128 v[136:139], v97
	ds_read_b128 v[140:143], v97 offset:8192
	ds_read_b128 v[144:147], v98
	ds_read_b128 v[148:151], v98 offset:8192
	s_setprio 1
	s_waitcnt lgkmcnt(7)
	v_mfma_f32_32x32x16_bf16 v[96:111], v[8:11], v[160:163], 0
	s_waitcnt lgkmcnt(6)
	v_mfma_f32_32x32x16_bf16 v[112:127], v[12:15], v[160:163], 0
	s_waitcnt lgkmcnt(5)
	v_mfma_f32_32x32x16_bf16 v[96:111], v[128:131], v[164:167], v[96:111]
	s_waitcnt lgkmcnt(4)
	v_mfma_f32_32x32x16_bf16 v[112:127], v[132:135], v[164:167], v[112:127]
	s_waitcnt lgkmcnt(3)
	v_mfma_f32_32x32x16_bf16 v[96:111], v[136:139], v[168:171], v[96:111]
	s_waitcnt lgkmcnt(2)
	v_mfma_f32_32x32x16_bf16 v[112:127], v[140:143], v[168:171], v[112:127]
	s_waitcnt lgkmcnt(1)
	v_mfma_f32_32x32x16_bf16 v[96:111], v[144:147], v[172:175], v[96:111]
	s_waitcnt lgkmcnt(0)
	v_mfma_f32_32x32x16_bf16 v[112:127], v[148:151], v[172:175], v[112:127]
	s_setprio 0
	s_and_b64 vcc, exec, s[78:79]
	s_cbranch_vccnz .Latt_nodma
	s_add_i32 s80, s14, 0x8000
	v_lshl_add_u64 v[152:153], s[96:97], 0, v[4:5]
	s_mov_b64 s[16:17], 0x9e82000
	s_and_b32 s80, s80, 0xc000
	v_lshl_add_u64 v[154:155], v[152:153], 0, s[16:17]
	s_add_i32 s81, s80, s59
	s_mov_b32 m0, s81
	v_lshl_add_u64 v[156:157], s[96:97], 0, v[2:3]
	global_load_lds_dwordx4 v[154:155], off
	s_mov_b64 s[16:17], 0x9f42000
	s_addk_i32 s81, 0x2000
	v_lshl_add_u64 v[152:153], v[152:153], 0, s[16:17]
	s_mov_b32 m0, s81
	s_mov_b64 s[16:17], 0x21a00180
	global_load_lds_dwordx4 v[152:153], off
	v_lshl_add_u64 v[158:159], v[156:157], 0, s[16:17]
	s_add_i32 s81, s80, s54
	s_mov_b32 m0, s81
	s_mov_b64 s[16:17], 0x21c00180
	global_load_lds_dwordx4 v[158:159], off
	v_lshl_add_u64 v[156:157], v[156:157], 0, s[16:17]
	s_addk_i32 s81, 0x2000
	s_mov_b32 m0, s81
	s_nop 0
	global_load_lds_dwordx4 v[156:157], off
	s_branch .Latt_dmadone
.Latt_nodma:
	s_nop 6
